# rsq fix-up removal in the HGRN2 pass-2 output normalisation (8 sites), on top of v93
# speedup vs baseline: 1.0159x; 1.0028x over previous
; __device__ __forceinline__ float frcp(float x) { return __builtin_amdgcn_rcpf(x); }
; __device__ __forceinline__ unsigned pk2(float a, float b) { f32x2v v = {a, b}; b16x2v r = __builtin_convertvector(v, b16x2v); return __builtin_bit_cast(unsigned, r); }
; template <bool FULL>
; __device__ __forceinline__ void hgrn_seg(const Params& p, unsigned char* lds, int b, int h, int seg) {
;     ...
;             float bl[8]; float run = 0.f;
; #pragma unroll
;             for (int i = 0; i < 8; ++i) { run += lf[i]; bl[i] = run; }
;             const int kk = lane & 15;
;             const float t0 = __shfl(run, kk), t1 = __shfl(run, kk + 16), t2 = __shfl(run, kk + 32), t3 = __shfl(run, kk + 48);
;             const float off = (tg > 0 ? t0 : 0.f) + (tg > 1 ? t1 : 0.f) + (tg > 2 ? t2 : 0.f);
;             const float blast = (t0 + t1) + (t2 + t3), dd = __builtin_amdgcn_exp2f(blast);
;             bseg += blast;
;             float kd[8];
; #pragma unroll
;             for (int i = 0; i < 8; ++i) { const float eb = __builtin_amdgcn_exp2f(bl[i] + off), einv = frcp(eb), kf = __uint_as_float(kq[i] << 16);
;                 kd[i] = kf * (dd * einv);
;                 if (FULL) { *(bf16_t*)(buf + HB_QD + ((8 * tg + i) * QP + pk) * 2) = (bf16_t)(pk2(__uint_as_float(qq[i] << 16) * eb, 0.f) & 0xffffu); *(bf16_t*)(buf + HB_KI + ((8 * tg + i) * QP + pk) * 2) = (bf16_t)(pk2(kf * einv, 0.f) & 0xffffu); } }
;             u32x4 kw; kw.x = pk2(kd[0], kd[1]); kw.y = pk2(kd[2], kd[3]); kw.z = pk2(kd[4], kd[5]); kw.w = pk2(kd[6], kd[7]);
;             *(u32x4*)(buf + HB_KD + (pk * TP + 8 * tg) * 2) = kw;
;             u32x4 vw; vw.x = vv[0] | (vv[1] << 16); vw.y = vv[2] | (vv[3] << 16); vw.z = vv[4] | (vv[5] << 16); vw.w = vv[6] | (vv[7] << 16);
;             *(u32x4*)(buf + HB_VT + (pk * TP + 8 * tg) * 2) = vw;
;             if (tg == 0) *(float*)(buf + HB_DV + pk * 4) = dd;
.LBB0_474:
	v_add_f32_e32 v32, 0, v142
	v_add_f32_e32 v142, v32, v149
	s_waitcnt vmcnt(7)
	v_add_f32_e32 v149, v142, v157
	v_add_f32_e32 v153, v149, v153
	s_waitcnt vmcnt(6)
	v_add_f32_e32 v157, v153, v159
	s_waitcnt vmcnt(5)
	v_add_f32_e32 v159, v157, v162
	v_add_f32_e32 v161, v159, v161
	v_add_f32_e32 v164, v161, v163
	ds_bpermute_b32 v44, v73, v164
	ds_bpermute_b32 v46, v133, v164
	ds_bpermute_b32 v45, v134, v164
	ds_bpermute_b32 v47, v135, v164
	s_and_b32 s83, s95, 1
	s_waitcnt lgkmcnt(3)
	v_cndmask_b32_e64 v162, v44, 0, s[6:7]
	s_waitcnt lgkmcnt(2)
	v_cndmask_b32_e64 v163, 0, v46, s[8:9]
	v_add_f32_e32 v162, v162, v163
	s_waitcnt lgkmcnt(1)
	v_cndmask_b32_e64 v163, 0, v45, s[10:11]
	v_add_f32_e32 v165, v162, v163
	v_add_f32_e32 v32, v32, v165
	v_exp_f32_e32 v162, v32
	s_waitcnt lgkmcnt(0)
	v_pk_add_f32 v[44:45], v[44:45], v[46:47]
	v_add_f32_e32 v46, v142, v165
	v_add_f32_e32 v32, v44, v45
	v_rcp_f32_e32 v44, v162
	v_exp_f32_e32 v142, v46
	s_mul_i32 s62, s83, 0x9600
	v_lshlrev_b32_e32 v45, 16, v145
	s_add_i32 s82, s62, 0
	v_mul_f32_e32 v45, v162, v45
	v_cvt_pk_bf16_f32 v45, v45, s0
	v_add_u32_e32 v145, s82, v79
	v_lshlrev_b32_e32 v46, 16, v43
	v_exp_f32_e32 v32, v32
	ds_write_b16 v145, v45
	v_rcp_f32_e32 v45, v142
	v_and_b32_e32 v47, 0xffff0000, v43
	v_mul_f32_e32 v43, v44, v46
	v_cvt_pk_bf16_f32 v43, v43, s0
	ds_write_b16 v145, v43 offset:8704
	v_lshlrev_b32_e32 v43, 16, v144
	v_mul_f32_e32 v43, v142, v43
	v_pk_mul_f32 v[162:163], v[32:33], v[44:45] op_sel_hi:[0,1]
	v_cvt_pk_bf16_f32 v43, v43, s0
	v_add_u32_e32 v44, s82, v80
	ds_write_b16 v44, v43
	v_add_f32_e32 v43, v149, v165
	v_exp_f32_e32 v43, v43
	v_mul_f32_e32 v45, v45, v47
	v_cvt_pk_bf16_f32 v45, v45, s0
	ds_write_b16 v44, v45 offset:8704
	v_lshlrev_b32_e32 v45, 16, v148
	v_rcp_f32_e32 v44, v43
	v_mul_f32_e32 v43, v43, v45
	v_add_f32_e32 v45, v153, v165
	v_exp_f32_e32 v142, v45
	v_pk_mul_f32 v[162:163], v[162:163], v[46:47]
	v_cvt_pk_bf16_f32 v43, v43, s0
	v_add_u32_e32 v46, s82, v82
	v_rcp_f32_e32 v45, v142
	ds_write_b16 v46, v43
	v_and_b32_e32 v43, 0xffff0000, v42
	v_lshlrev_b32_e32 v42, 16, v42
	v_mul_f32_e32 v47, v44, v42
	v_cvt_pk_bf16_f32 v47, v47, s0
	ds_write_b16 v46, v47 offset:8704
	v_pk_mul_f32 v[46:47], v[32:33], v[44:45] op_sel_hi:[0,1]
	v_pk_mul_f32 v[46:47], v[46:47], v[42:43]
	v_lshlrev_b32_e32 v42, 16, v147
	v_mul_f32_e32 v42, v142, v42
	v_cvt_pk_bf16_f32 v42, v42, s0
	v_add_u32_e32 v44, s82, v83
	ds_write_b16 v44, v42
	v_add_f32_e32 v42, v157, v165
	v_exp_f32_e32 v142, v42
	v_mul_f32_e32 v42, v45, v43
	v_cvt_pk_bf16_f32 v42, v42, s0
	ds_write_b16 v44, v42 offset:8704
	v_lshlrev_b32_e32 v43, 16, v152
	v_add_f32_e32 v44, v159, v165
	v_rcp_f32_e32 v42, v142
	v_mul_f32_e32 v43, v142, v43
	v_exp_f32_e32 v142, v44
	v_cvt_pk_bf16_f32 v43, v43, s0
	v_add_u32_e32 v144, s82, v84
	v_lshlrev_b32_e32 v44, 16, v41
	ds_write_b16 v144, v43
	v_rcp_f32_e32 v43, v142
	v_and_b32_e32 v45, 0xffff0000, v41
	v_mul_f32_e32 v41, v42, v44
	v_cvt_pk_bf16_f32 v41, v41, s0
	ds_write_b16 v144, v41 offset:8704
	v_lshlrev_b32_e32 v41, 16, v154
	v_mul_f32_e32 v41, v142, v41
	v_pk_mul_f32 v[144:145], v[32:33], v[42:43] op_sel_hi:[0,1]
	v_cvt_pk_bf16_f32 v41, v41, s0
	v_add_u32_e32 v42, s82, v85
	ds_write_b16 v42, v41
	v_add_f32_e32 v41, v161, v165
	v_exp_f32_e32 v41, v41
	v_mul_f32_e32 v43, v43, v45
	v_cvt_pk_bf16_f32 v43, v43, s0
	ds_write_b16 v42, v43 offset:8704
	v_lshlrev_b32_e32 v43, 16, v156
	v_rcp_f32_e32 v42, v41
	v_mul_f32_e32 v41, v41, v43
	v_add_f32_e32 v43, v164, v165
	v_exp_f32_e32 v142, v43
	v_pk_mul_f32 v[144:145], v[144:145], v[44:45]
	v_cvt_pk_bf16_f32 v41, v41, s0
	v_add_u32_e32 v44, s82, v86
	v_rcp_f32_e32 v43, v142
	ds_write_b16 v44, v41
	v_and_b32_e32 v41, 0xffff0000, v40
	v_lshlrev_b32_e32 v40, 16, v40
	v_mul_f32_e32 v45, v42, v40
	v_cvt_pk_bf16_f32 v45, v45, s0
	ds_write_b16 v44, v45 offset:8704
	v_pk_mul_f32 v[44:45], v[32:33], v[42:43] op_sel_hi:[0,1]
	v_pk_mul_f32 v[44:45], v[44:45], v[40:41]
	v_lshlrev_b32_e32 v40, 16, v155
	v_mul_f32_e32 v40, v142, v40
	v_cvt_pk_bf16_f32 v40, v40, s0
	v_add_u32_e32 v42, s82, v87
	ds_write_b16 v42, v40
	v_mul_f32_e32 v40, v43, v41
	v_cvt_pk_bf16_f32 v40, v40, s0
	ds_write_b16 v42, v40 offset:8704
	v_cvt_pk_bf16_f32 v40, v162, v163
	v_cvt_pk_bf16_f32 v41, v46, v47
	v_cvt_pk_bf16_f32 v42, v144, v145
	v_cvt_pk_bf16_f32 v43, v44, v45
	v_add_u32_e32 v44, s82, v75
	ds_write_b128 v44, v[40:43] offset:17408
	v_lshlrev_b32_e32 v40, 16, v72
	v_lshlrev_b32_e32 v41, 16, v81
	v_lshlrev_b32_e32 v42, 16, v146
	v_lshlrev_b32_e32 v43, 16, v151
	v_or_b32_sdwa v40, v40, v70 dst_sel:DWORD dst_unused:UNUSED_PAD src0_sel:DWORD src1_sel:WORD_0
	v_or_b32_sdwa v41, v41, v74 dst_sel:DWORD dst_unused:UNUSED_PAD src0_sel:DWORD src1_sel:WORD_0
	v_or_b32_sdwa v42, v42, v143 dst_sel:DWORD dst_unused:UNUSED_PAD src0_sel:DWORD src1_sel:WORD_0
	v_or_b32_sdwa v43, v43, v150 dst_sel:DWORD dst_unused:UNUSED_PAD src0_sel:DWORD src1_sel:WORD_0
	ds_write_b128 v44, v[40:43] offset:27648
	s_and_saveexec_b64 s[62:63], s[6:7]
	v_add_u32_e32 v40, s82, v76
	ds_write_b32 v40, v32 offset:37888
	s_or_b64 exec, exec, s[62:63]
	s_cmpk_lg_i32 s64, 0x100
	s_cselect_b32 s62, s64, 0xe0
	s_add_i32 s62, s62, s70
	v_or_b32_e32 v40, s62, v99
	v_ashrrev_i32_e32 v41, 31, v40
	v_lshlrev_b64 v[40:41], 9, v[40:41]
	v_lshl_add_u64 v[40:41], v[50:51], 0, v[40:41]
	v_lshl_add_u64 v[42:43], v[40:41], 2, s[90:91]
	v_add_co_u32_e32 v146, vcc, s92, v42
	v_lshlrev_b64 v[40:41], 1, v[40:41]
	s_nop 0
	v_addc_co_u32_e32 v147, vcc, 0, v43, vcc
	v_add_co_u32_e32 v150, vcc, s0, v42
	v_lshl_add_u64 v[44:45], s[80:81], 0, v[40:41]
	v_lshl_add_u64 v[46:47], s[68:69], 0, v[40:41]
	v_lshl_add_u64 v[40:41], s[84:85], 0, v[40:41]
; #define LDS_BARRIER() do { asm volatile("s_waitcnt lgkmcnt(0)" ::: "memory"); __builtin_amdgcn_s_barrier(); asm volatile("" ::: "memory"); } while (0)
; template <bool FULL>
; __device__ __forceinline__ void hgrn_seg(const Params& p, unsigned char* lds, int b, int h, int seg) {
;     ...
;         { const int cn = c + 1 < NCH ? c + 1 : c; HG_LOAD(cn); }
;         LDS_BARRIER();
	v_addc_co_u32_e32 v151, vcc, 0, v43, vcc
	global_load_dword v142, v[42:43], off
	global_load_ushort v164, v[44:45], off
	global_load_ushort v70, v[46:47], off
	global_load_ushort v145, v[40:41], off
	global_load_dword v149, v[42:43], off offset:2048
	global_load_ushort v165, v[44:45], off offset:1024
	global_load_ushort v72, v[46:47], off offset:1024
	global_load_ushort v144, v[40:41], off offset:1024
	global_load_dword v157, v[150:151], off offset:-4096
	global_load_ushort v166, v[44:45], off offset:2048
	global_load_ushort v74, v[46:47], off offset:2048
	global_load_ushort v148, v[40:41], off offset:2048
	global_load_dword v153, v[146:147], off offset:2048
	global_load_ushort v167, v[44:45], off offset:3072
	global_load_ushort v81, v[46:47], off offset:3072
	s_nop 0
	global_load_ushort v147, v[40:41], off offset:3072
	global_load_dword v159, v[150:151], off
	v_add_co_u32_e32 v44, vcc, s92, v44
	s_add_i32 s62, s62, s94
	s_nop 0
	v_addc_co_u32_e32 v45, vcc, 0, v45, vcc
	v_add_co_u32_e32 v46, vcc, s92, v46
	s_ashr_i32 s63, s62, 31
	s_nop 0
	v_addc_co_u32_e32 v47, vcc, 0, v47, vcc
	v_add_co_u32_e32 v40, vcc, s92, v40
	global_load_ushort v168, v[44:45], off
	global_load_ushort v143, v[46:47], off
	v_addc_co_u32_e32 v41, vcc, 0, v41, vcc
	v_add_co_u32_e32 v42, vcc, s1, v42
	global_load_ushort v152, v[40:41], off
	global_load_dword v162, v[150:151], off offset:2048
	global_load_ushort v169, v[44:45], off offset:1024
	global_load_ushort v146, v[46:47], off offset:1024
	global_load_ushort v154, v[40:41], off offset:1024
	v_addc_co_u32_e32 v43, vcc, 0, v43, vcc
	s_lshl_b64 vcc, s[62:63], 10
	global_load_dword v161, v[42:43], off
	global_load_ushort v172, v[44:45], off offset:2048
	global_load_ushort v150, v[46:47], off offset:2048
	global_load_ushort v156, v[40:41], off offset:2048
	global_load_dword v163, v[42:43], off offset:2048
	global_load_ushort v173, v[44:45], off offset:3072
	global_load_ushort v151, v[46:47], off offset:3072
	global_load_ushort v155, v[40:41], off offset:3072
	v_lshl_add_u64 v[40:41], v[64:65], 0, vcc
	s_or_b32 vcc_lo, s62, 1
	s_ashr_i32 vcc_hi, vcc_lo, 31
	s_lshl_b64 vcc, vcc, 10
	global_load_ushort v170, v[40:41], off
	global_load_ushort v171, v[40:41], off offset:128
	v_lshl_add_u64 v[40:41], v[64:65], 0, vcc
	s_or_b32 vcc_lo, s62, 2
	s_ashr_i32 vcc_hi, vcc_lo, 31
	s_or_b32 s62, s62, 3
	s_lshl_b64 vcc, vcc, 10
	s_ashr_i32 s63, s62, 31
	global_load_ushort v174, v[40:41], off
	global_load_ushort v175, v[40:41], off offset:128
	v_lshl_add_u64 v[40:41], v[64:65], 0, vcc
	s_lshl_b64 s[62:63], s[62:63], 10
	global_load_ushort v177, v[40:41], off
	global_load_ushort v180, v[40:41], off offset:128
	v_lshl_add_u64 v[40:41], v[64:65], 0, s[62:63]
	global_load_ushort v181, v[40:41], off
	global_load_ushort v182, v[40:41], off offset:128
	s_waitcnt lgkmcnt(0)
	s_barrier
	s_cmp_eq_u32 s64, 32
	s_cbranch_scc1 .LBB0_478
	s_and_b32 s62, s65, 0x8000
	s_add_i32 s62, s62, 0
	s_add_i32 s62, s62, 0x12c00
	v_lshl_add_u32 v32, v60, 2, s62
	ds_read2st64_b32 v[40:41], v32 offset1:1
	ds_read2st64_b32 v[42:43], v32 offset0:64 offset1:65
	s_waitcnt lgkmcnt(0)
	v_pk_add_f32 v[40:41], v[40:41], v[42:43]
	s_nop 0
	v_pk_mul_f32 v[42:43], v[40:41], v[40:41]
	s_nop 0
	v_add_f32_e32 v32, v42, v43
	s_nop 1
	v_add_f32_dpp v32, v32, v32 quad_perm:[1,0,3,2] row_mask:0xf bank_mask:0xf bound_ctrl:1
	s_nop 1
	v_add_f32_dpp v32, v32, v32 quad_perm:[2,3,0,1] row_mask:0xf bank_mask:0xf bound_ctrl:1
	s_nop 1
	v_add_f32_dpp v32, v32, v32 row_half_mirror row_mask:0xf bank_mask:0xf bound_ctrl:1
	s_nop 1
	v_add_f32_dpp v32, v32, v32 row_mirror row_mask:0xf bank_mask:0xf bound_ctrl:1
	s_nop 0
	v_readlane_b32 s63, v32, 16
	v_readlane_b32 s61, v32, 48
	v_readlane_b32 vcc_lo, v32, 0
	v_readlane_b32 vcc_hi, v32, 32
	v_mov_b32_e32 v42, s63
	v_mov_b32_e32 v43, s61
	v_pk_add_f32 v[42:43], vcc, v[42:43]
	s_add_i32 s63, s67, s64
	v_add_f32_e32 v32, v42, v43
	v_fmamk_f32 v32, v32, 0x3c000000, v131
	s_nop 0
	v_rsq_f32_e32 v32, v32
	s_nop 0
	s_sub_i32 vcc_lo, s63, 64
	s_ashr_i32 vcc_hi, vcc_lo, 31
	v_mul_f32_e32 v40, v40, v32
	v_mul_f32_e32 v32, v41, v32
	v_mul_f32_e32 v40, v66, v40
	s_lshl_b64 vcc, vcc, 11
	v_mul_f32_e32 v32, v61, v32
	v_mul_f32_e32 v40, v158, v40
	v_lshl_add_u64 v[42:43], v[62:63], 0, vcc
	v_mul_f32_e32 v32, v39, v32
	v_cvt_pk_bf16_f32 v40, v40, v51
	global_store_short v[42:43], v40, off
	v_cvt_pk_bf16_f32 v32, v32, v51
	global_store_short v[42:43], v32, off offset:128
	v_lshl_add_u32 v32, v71, 2, s62
	ds_read2st64_b32 v[40:41], v32 offset1:1
	ds_read2st64_b32 v[42:43], v32 offset0:64 offset1:65
	s_waitcnt lgkmcnt(0)
	v_pk_add_f32 v[40:41], v[40:41], v[42:43]
	s_nop 0
	v_pk_mul_f32 v[42:43], v[40:41], v[40:41]
	s_nop 0
	v_add_f32_e32 v32, v42, v43
	s_nop 1
	v_add_f32_dpp v32, v32, v32 quad_perm:[1,0,3,2] row_mask:0xf bank_mask:0xf bound_ctrl:1
	s_nop 1
	v_add_f32_dpp v32, v32, v32 quad_perm:[2,3,0,1] row_mask:0xf bank_mask:0xf bound_ctrl:1
	s_nop 1
	v_add_f32_dpp v32, v32, v32 row_half_mirror row_mask:0xf bank_mask:0xf bound_ctrl:1
	s_nop 1
	v_add_f32_dpp v32, v32, v32 row_mirror row_mask:0xf bank_mask:0xf bound_ctrl:1
	s_nop 0
	v_readlane_b32 s61, v32, 16
	v_readlane_b32 s56, v32, 48
	v_readlane_b32 vcc_lo, v32, 0
	v_readlane_b32 vcc_hi, v32, 32
	v_mov_b32_e32 v42, s61
	v_mov_b32_e32 v43, s56
	v_pk_add_f32 v[42:43], vcc, v[42:43]
	s_nop 0
	v_add_f32_e32 v32, v42, v43
	v_fmamk_f32 v32, v32, 0x3c000000, v131
	s_nop 0
	v_rsq_f32_e32 v32, v32
	s_nop 0
	s_sub_i32 vcc_lo, s63, 63
	v_mul_f32_e32 v39, v40, v32
	s_ashr_i32 vcc_hi, vcc_lo, 31
	v_mul_f32_e32 v39, v66, v39
	v_mul_f32_e32 v32, v41, v32
	v_mul_f32_e32 v38, v38, v39
	s_lshl_b64 vcc, vcc, 11
	v_mul_f32_e32 v32, v61, v32
	v_cvt_pk_bf16_f32 v40, v38, v51
	v_lshl_add_u64 v[38:39], v[62:63], 0, vcc
	v_mul_f32_e32 v32, v37, v32
	global_store_short v[38:39], v40, off
	v_cvt_pk_bf16_f32 v32, v32, v51
	global_store_short v[38:39], v32, off offset:128
	v_lshl_add_u32 v32, v69, 2, s62
	ds_read2st64_b32 v[38:39], v32 offset1:1
	ds_read2st64_b32 v[40:41], v32 offset0:64 offset1:65
	s_waitcnt lgkmcnt(0)
	v_pk_add_f32 v[38:39], v[38:39], v[40:41]
	s_nop 0
	v_pk_mul_f32 v[40:41], v[38:39], v[38:39]
	s_nop 0
	v_add_f32_e32 v32, v40, v41
	s_nop 1
	v_add_f32_dpp v32, v32, v32 quad_perm:[1,0,3,2] row_mask:0xf bank_mask:0xf bound_ctrl:1
	s_nop 1
	v_add_f32_dpp v32, v32, v32 quad_perm:[2,3,0,1] row_mask:0xf bank_mask:0xf bound_ctrl:1
	s_nop 1
	v_add_f32_dpp v32, v32, v32 row_half_mirror row_mask:0xf bank_mask:0xf bound_ctrl:1
	s_nop 1
	v_add_f32_dpp v32, v32, v32 row_mirror row_mask:0xf bank_mask:0xf bound_ctrl:1
	s_nop 0
	v_readlane_b32 s56, v32, 16
	v_readlane_b32 s57, v32, 48
	v_readlane_b32 vcc_lo, v32, 0
	v_readlane_b32 vcc_hi, v32, 32
	v_mov_b32_e32 v40, s56
	v_mov_b32_e32 v41, s57
	v_pk_add_f32 v[40:41], vcc, v[40:41]
	s_nop 0
	v_add_f32_e32 v32, v40, v41
	v_fmamk_f32 v32, v32, 0x3c000000, v131
	s_nop 0
	v_rsq_f32_e32 v32, v32
	s_nop 0
	s_sub_i32 vcc_lo, s63, 62
	v_mul_f32_e32 v37, v38, v32
	s_ashr_i32 vcc_hi, vcc_lo, 31
	v_mul_f32_e32 v37, v66, v37
	v_mul_f32_e32 v32, v39, v32
	v_mul_f32_e32 v36, v36, v37
	s_lshl_b64 vcc, vcc, 11
	v_mul_f32_e32 v32, v61, v32
	v_cvt_pk_bf16_f32 v38, v36, v51
	v_lshl_add_u64 v[36:37], v[62:63], 0, vcc
	v_mul_f32_e32 v32, v35, v32
	global_store_short v[36:37], v38, off
	v_cvt_pk_bf16_f32 v32, v32, v51
	global_store_short v[36:37], v32, off offset:128
	v_lshl_add_u32 v32, v68, 2, s62
	ds_read2st64_b32 v[36:37], v32 offset1:1
	ds_read2st64_b32 v[38:39], v32 offset0:64 offset1:65
	s_sub_i32 s62, s63, 61
	s_ashr_i32 s63, s62, 31
	s_lshl_b64 s[62:63], s[62:63], 11
	s_waitcnt lgkmcnt(0)
	v_pk_add_f32 v[36:37], v[36:37], v[38:39]
	s_nop 0
	v_pk_mul_f32 v[38:39], v[36:37], v[36:37]
	s_nop 0
	v_add_f32_e32 v32, v38, v39
	s_nop 1
	v_add_f32_dpp v32, v32, v32 quad_perm:[1,0,3,2] row_mask:0xf bank_mask:0xf bound_ctrl:1
	s_nop 1
	v_add_f32_dpp v32, v32, v32 quad_perm:[2,3,0,1] row_mask:0xf bank_mask:0xf bound_ctrl:1
	s_nop 1
	v_add_f32_dpp v32, v32, v32 row_half_mirror row_mask:0xf bank_mask:0xf bound_ctrl:1
	s_nop 1
	v_add_f32_dpp v32, v32, v32 row_mirror row_mask:0xf bank_mask:0xf bound_ctrl:1
	s_nop 0
	v_readlane_b32 s56, v32, 16
	v_readlane_b32 s57, v32, 48
	v_readlane_b32 vcc_lo, v32, 0
	v_readlane_b32 vcc_hi, v32, 32
	v_mov_b32_e32 v38, s56
	v_mov_b32_e32 v39, s57
	v_pk_add_f32 v[38:39], vcc, v[38:39]
	s_nop 0
	v_add_f32_e32 v32, v38, v39
	v_fmamk_f32 v32, v32, 0x3c000000, v131
	s_nop 0
	v_rsq_f32_e32 v32, v32
	s_nop 0
	v_mul_f32_e32 v35, v36, v32
	v_mul_f32_e32 v35, v66, v35
	v_mul_f32_e32 v32, v37, v32
	v_mul_f32_e32 v34, v34, v35
	v_mul_f32_e32 v32, v61, v32
	v_cvt_pk_bf16_f32 v36, v34, v51
	v_lshl_add_u64 v[34:35], v[62:63], 0, s[62:63]
	v_mul_f32_e32 v32, v33, v32
	global_store_short v[34:35], v36, off
	v_cvt_pk_bf16_f32 v32, v32, v51
	global_store_short v[34:35], v32, off offset:128

; #define LDS_BARRIER() do { asm volatile("s_waitcnt lgkmcnt(0)" ::: "memory"); __builtin_amdgcn_s_barrier(); asm volatile("" ::: "memory"); } while (0)
; template <bool FULL>
; __device__ __forceinline__ void hgrn_seg(const Params& p, unsigned char* lds, int b, int h, int seg) {
;     ...
;     if (FULL) { LDS_BARRIER(); HG_FINALIZE(NCH - 1); }
.LBB0_480:
	v_lshlrev_b32_e32 v32, 2, v60
	s_waitcnt lgkmcnt(0)
	s_barrier
	v_add_u32_e32 v40, s89, v32
	v_add_u32_e32 v41, s33, v32
	v_or_b32_e32 v32, 0x100, v32
	ds_read_b32 v40, v40
	ds_read_b32 v42, v41
	v_add_u32_e32 v41, s89, v32
	v_add_u32_e32 v32, s33, v32
	ds_read_b32 v41, v41
	ds_read_b32 v43, v32
	s_or_b32 s4, s70, 0xe0
	s_mov_b64 s[82:83], s[58:59]
	s_waitcnt lgkmcnt(0)
	v_pk_add_f32 v[40:41], v[40:41], v[42:43]
	s_nop 0
	v_pk_mul_f32 v[42:43], v[40:41], v[40:41]
	s_nop 0
	v_add_f32_e32 v32, v42, v43
	s_nop 1
	v_add_f32_dpp v32, v32, v32 quad_perm:[1,0,3,2] row_mask:0xf bank_mask:0xf bound_ctrl:1
	s_nop 1
	v_add_f32_dpp v32, v32, v32 quad_perm:[2,3,0,1] row_mask:0xf bank_mask:0xf bound_ctrl:1
	s_nop 1
	v_add_f32_dpp v32, v32, v32 row_half_mirror row_mask:0xf bank_mask:0xf bound_ctrl:1
	s_nop 1
	v_add_f32_dpp v32, v32, v32 row_mirror row_mask:0xf bank_mask:0xf bound_ctrl:1
	s_nop 0
	v_readlane_b32 s64, v32, 16
	v_readlane_b32 s65, v32, 48
	v_readlane_b32 s62, v32, 0
	v_readlane_b32 s63, v32, 32
	v_mov_b32_e32 v42, s64
	v_mov_b32_e32 v43, s65
	v_pk_add_f32 v[42:43], s[62:63], v[42:43]
	s_add_i32 s62, s94, s4
	v_add_f32_e32 v32, v42, v43
	v_fmamk_f32 v32, v32, 0x3c000000, v131
	s_ashr_i32 s63, s62, 31
	v_rsq_f32_e32 v32, v32
	s_lshl_b64 s[62:63], s[62:63], 11
	v_mul_f32_e32 v40, v40, v32
	v_mul_f32_e32 v32, v41, v32
	v_mul_f32_e32 v40, v66, v40
	v_mul_f32_e32 v32, v61, v32
	v_mul_f32_e32 v40, v40, v158
	v_lshl_add_u64 v[42:43], v[62:63], 0, s[62:63]
	v_mul_f32_e32 v32, v32, v39
	v_cvt_pk_bf16_f32 v40, v40, v51
	global_store_short v[42:43], v40, off
	v_cvt_pk_bf16_f32 v32, v32, v51
	global_store_short v[42:43], v32, off offset:128
	v_lshlrev_b32_e32 v32, 2, v71
	v_add_u32_e32 v39, s89, v32
	ds_read_b32 v40, v39
	v_add_u32_e32 v39, s33, v32
	v_or_b32_e32 v32, 0x100, v32
	ds_read_b32 v42, v39
	v_add_u32_e32 v39, s89, v32
	v_add_u32_e32 v32, s33, v32
	ds_read_b32 v41, v39
	ds_read_b32 v43, v32
	s_waitcnt lgkmcnt(0)
	v_pk_add_f32 v[40:41], v[40:41], v[42:43]
	s_nop 0
	v_pk_mul_f32 v[42:43], v[40:41], v[40:41]
	s_nop 0
	v_add_f32_e32 v32, v42, v43
	s_nop 1
	v_add_f32_dpp v32, v32, v32 quad_perm:[1,0,3,2] row_mask:0xf bank_mask:0xf bound_ctrl:1
	s_nop 1
	v_add_f32_dpp v32, v32, v32 quad_perm:[2,3,0,1] row_mask:0xf bank_mask:0xf bound_ctrl:1
	s_nop 1
	v_add_f32_dpp v32, v32, v32 row_half_mirror row_mask:0xf bank_mask:0xf bound_ctrl:1
	s_nop 1
	v_add_f32_dpp v32, v32, v32 row_mirror row_mask:0xf bank_mask:0xf bound_ctrl:1
	s_nop 0
	v_readlane_b32 s64, v32, 16
	v_readlane_b32 s65, v32, 48
	v_readlane_b32 s62, v32, 0
	v_readlane_b32 s63, v32, 32
	v_mov_b32_e32 v42, s64
	v_mov_b32_e32 v43, s65
	v_pk_add_f32 v[42:43], s[62:63], v[42:43]
	s_add_i32 s62, s71, s4
	v_add_f32_e32 v32, v42, v43
	v_fmamk_f32 v32, v32, 0x3c000000, v131
	s_ashr_i32 s63, s62, 31
	v_rsq_f32_e32 v32, v32
	s_lshl_b64 s[62:63], s[62:63], 11
	v_mul_f32_e32 v39, v40, v32
	v_mul_f32_e32 v39, v66, v39
	v_mul_f32_e32 v32, v41, v32
	v_mul_f32_e32 v38, v39, v38
	v_mul_f32_e32 v32, v61, v32
	v_cvt_pk_bf16_f32 v40, v38, v51
	v_lshl_add_u64 v[38:39], v[62:63], 0, s[62:63]
	v_mul_f32_e32 v32, v32, v37
	global_store_short v[38:39], v40, off
	v_cvt_pk_bf16_f32 v32, v32, v51
	global_store_short v[38:39], v32, off offset:128
	v_lshlrev_b32_e32 v32, 2, v69
	v_add_u32_e32 v37, s89, v32
	ds_read_b32 v38, v37
	v_add_u32_e32 v37, s33, v32
	v_or_b32_e32 v32, 0x100, v32
	ds_read_b32 v40, v37
	v_add_u32_e32 v37, s89, v32
	v_add_u32_e32 v32, s33, v32
	ds_read_b32 v39, v37
	ds_read_b32 v41, v32
	s_waitcnt lgkmcnt(0)
	v_pk_add_f32 v[38:39], v[38:39], v[40:41]
	s_nop 0
	v_pk_mul_f32 v[40:41], v[38:39], v[38:39]
	s_nop 0
	v_add_f32_e32 v32, v40, v41
	s_nop 1
	v_add_f32_dpp v32, v32, v32 quad_perm:[1,0,3,2] row_mask:0xf bank_mask:0xf bound_ctrl:1
	s_nop 1
	v_add_f32_dpp v32, v32, v32 quad_perm:[2,3,0,1] row_mask:0xf bank_mask:0xf bound_ctrl:1
	s_nop 1
	v_add_f32_dpp v32, v32, v32 row_half_mirror row_mask:0xf bank_mask:0xf bound_ctrl:1
	s_nop 1
	v_add_f32_dpp v32, v32, v32 row_mirror row_mask:0xf bank_mask:0xf bound_ctrl:1
	s_nop 0
	v_readlane_b32 s64, v32, 16
	v_readlane_b32 s65, v32, 48
	v_readlane_b32 s62, v32, 0
	v_readlane_b32 s63, v32, 32
	v_mov_b32_e32 v40, s64
	v_mov_b32_e32 v41, s65
	v_pk_add_f32 v[40:41], s[62:63], v[40:41]
	s_add_i32 s62, s60, s4
	v_add_f32_e32 v32, v40, v41
	v_fmamk_f32 v32, v32, 0x3c000000, v131
	s_ashr_i32 s63, s62, 31
	v_rsq_f32_e32 v32, v32
	s_lshl_b64 s[62:63], s[62:63], 11
	v_mul_f32_e32 v37, v38, v32
	v_mul_f32_e32 v37, v66, v37
	v_mul_f32_e32 v32, v39, v32
	v_mul_f32_e32 v36, v37, v36
	v_mul_f32_e32 v32, v61, v32
	v_cvt_pk_bf16_f32 v38, v36, v51
	v_lshl_add_u64 v[36:37], v[62:63], 0, s[62:63]
	v_mul_f32_e32 v32, v32, v35
	global_store_short v[36:37], v38, off
	v_cvt_pk_bf16_f32 v32, v32, v51
	global_store_short v[36:37], v32, off offset:128
	v_lshlrev_b32_e32 v32, 2, v68
	v_add_u32_e32 v35, s89, v32
	ds_read_b32 v36, v35
	v_add_u32_e32 v35, s33, v32
	v_or_b32_e32 v32, 0x100, v32
	ds_read_b32 v38, v35
	v_add_u32_e32 v35, s89, v32
	v_add_u32_e32 v32, s33, v32
	ds_read_b32 v37, v35
	ds_read_b32 v39, v32
	s_waitcnt lgkmcnt(0)
	v_pk_add_f32 v[36:37], v[36:37], v[38:39]
	s_nop 0
	v_pk_mul_f32 v[38:39], v[36:37], v[36:37]
	s_nop 0
	v_add_f32_e32 v32, v38, v39
	s_nop 1
	v_add_f32_dpp v32, v32, v32 quad_perm:[1,0,3,2] row_mask:0xf bank_mask:0xf bound_ctrl:1
	s_nop 1
	v_add_f32_dpp v32, v32, v32 quad_perm:[2,3,0,1] row_mask:0xf bank_mask:0xf bound_ctrl:1
	s_nop 1
	v_add_f32_dpp v32, v32, v32 row_half_mirror row_mask:0xf bank_mask:0xf bound_ctrl:1
	s_nop 1
	v_add_f32_dpp v32, v32, v32 row_mirror row_mask:0xf bank_mask:0xf bound_ctrl:1
	s_nop 0
	v_readlane_b32 s60, v32, 16
	v_readlane_b32 s64, v32, 48
	v_readlane_b32 s62, v32, 0
	v_readlane_b32 s63, v32, 32
	v_mov_b32_e32 v38, s60
	v_mov_b32_e32 v39, s64
	v_pk_add_f32 v[38:39], s[62:63], v[38:39]
	s_add_i32 s62, s47, s4
	v_add_f32_e32 v32, v38, v39
	v_fmamk_f32 v32, v32, 0x3c000000, v131
	s_ashr_i32 s63, s62, 31
	v_rsq_f32_e32 v32, v32
	s_lshl_b64 s[62:63], s[62:63], 11
	s_cmp_eq_u32 s49, 7
	v_mul_f32_e32 v35, v36, v32
	v_mul_f32_e32 v35, v66, v35
	v_mul_f32_e32 v32, v37, v32
	v_mul_f32_e32 v34, v35, v34
	v_mul_f32_e32 v32, v61, v32
	v_cvt_pk_bf16_f32 v36, v34, v51
	v_lshl_add_u64 v[34:35], v[62:63], 0, s[62:63]
	v_mul_f32_e32 v32, v32, v33
	global_store_short v[34:35], v36, off
	v_cvt_pk_bf16_f32 v32, v32, v51
	global_store_short v[34:35], v32, off offset:128
	s_cbranch_scc0 .LBB0_482
; template <bool FULL>
; __device__ __forceinline__ void hgrn_seg(const Params& p, unsigned char* lds, int b, int h, int seg) {
;     ...
;     if (FULL) { if (seg == NSEG - 1) { float* so = p.out + O_SHP + (size_t)bh * DK * DV;
; #pragma unroll
;         for (int a = 0; a < 2; ++a)
; #pragma unroll
;             for (int g = 0; g < 4; ++g)
; #pragma unroll
;                 for (int i = 0; i < 4; ++i) so[(size_t)(32 * (2 * kh + a) + 8 * g + 4 * hh + i) * DV + 32 * vb + r] = S[a][4 * g + i]; }
	s_ashr_i32 s47, s46, 31
	s_lshl_b64 s[46:47], s[46:47], 16
	s_add_u32 s4, s86, s46
	v_readlane_b32 s46, v247, 52
	s_addc_u32 s47, s46, s47
	s_lshl_b32 s46, s50, 2
	s_add_u32 s46, s4, s46
	v_or_b32_e32 v32, s51, v100
	s_addc_u32 s47, s47, 0
	v_lshlrev_b32_e32 v50, 2, v48
	v_mov_b32_e32 v33, v51
	v_lshl_add_u64 v[34:35], s[46:47], 0, v[50:51]
	v_lshlrev_b64 v[36:37], 9, v[32:33]
	v_lshl_add_u64 v[36:37], v[34:35], 0, v[36:37]
	v_or_b32_e32 v50, 1, v32
	global_store_dword v[36:37], v16, off
	v_lshlrev_b64 v[36:37], 9, v[50:51]
	v_lshl_add_u64 v[36:37], v[34:35], 0, v[36:37]
	v_or_b32_e32 v50, 2, v32
	global_store_dword v[36:37], v17, off
	v_lshlrev_b64 v[16:17], 9, v[50:51]
	v_lshl_add_u64 v[16:17], v[34:35], 0, v[16:17]
	v_or_b32_e32 v50, 3, v32
	global_store_dword v[16:17], v18, off
	v_lshlrev_b64 v[16:17], 9, v[50:51]
	v_lshl_add_u64 v[16:17], v[34:35], 0, v[16:17]
	v_or_b32_e32 v50, 8, v32
	global_store_dword v[16:17], v19, off
	v_lshlrev_b64 v[16:17], 9, v[50:51]
	v_lshl_add_u64 v[16:17], v[34:35], 0, v[16:17]
	v_or_b32_e32 v50, 9, v32
	global_store_dword v[16:17], v20, off
	v_lshlrev_b64 v[16:17], 9, v[50:51]
	v_lshl_add_u64 v[16:17], v[34:35], 0, v[16:17]
	v_or_b32_e32 v50, 10, v32
	global_store_dword v[16:17], v21, off
	v_lshlrev_b64 v[16:17], 9, v[50:51]
	v_lshl_add_u64 v[16:17], v[34:35], 0, v[16:17]
	v_or_b32_e32 v50, 11, v32
	global_store_dword v[16:17], v22, off
	v_lshlrev_b64 v[16:17], 9, v[50:51]
	v_lshl_add_u64 v[16:17], v[34:35], 0, v[16:17]
	v_or_b32_e32 v50, 16, v32
	global_store_dword v[16:17], v23, off
	v_lshlrev_b64 v[16:17], 9, v[50:51]
	v_lshl_add_u64 v[16:17], v[34:35], 0, v[16:17]
	v_or_b32_e32 v50, 17, v32
	global_store_dword v[16:17], v24, off
	v_lshlrev_b64 v[16:17], 9, v[50:51]
	v_lshl_add_u64 v[16:17], v[34:35], 0, v[16:17]
	v_or_b32_e32 v50, 18, v32
	global_store_dword v[16:17], v25, off
	v_lshlrev_b64 v[16:17], 9, v[50:51]
	v_lshl_add_u64 v[16:17], v[34:35], 0, v[16:17]
	v_or_b32_e32 v50, 19, v32
	global_store_dword v[16:17], v26, off
	v_lshlrev_b64 v[16:17], 9, v[50:51]
	v_lshl_add_u64 v[16:17], v[34:35], 0, v[16:17]
	v_or_b32_e32 v50, 24, v32
	global_store_dword v[16:17], v27, off
	v_lshlrev_b64 v[16:17], 9, v[50:51]
	v_lshl_add_u64 v[16:17], v[34:35], 0, v[16:17]
	v_or_b32_e32 v50, 25, v32
	global_store_dword v[16:17], v28, off
	v_lshlrev_b64 v[16:17], 9, v[50:51]
	v_lshl_add_u64 v[16:17], v[34:35], 0, v[16:17]
	v_or_b32_e32 v50, 26, v32
	global_store_dword v[16:17], v29, off
	v_lshlrev_b64 v[16:17], 9, v[50:51]
	v_lshl_add_u64 v[16:17], v[34:35], 0, v[16:17]
	v_or_b32_e32 v50, 27, v32
	global_store_dword v[16:17], v30, off
	v_lshlrev_b64 v[16:17], 9, v[50:51]
	v_lshl_add_u64 v[16:17], v[34:35], 0, v[16:17]
	v_or_b32_e32 v50, 32, v32
	global_store_dword v[16:17], v31, off
	v_lshlrev_b64 v[16:17], 9, v[50:51]
	v_lshl_add_u64 v[16:17], v[34:35], 0, v[16:17]
	v_or_b32_e32 v50, 33, v32
	global_store_dword v[16:17], v0, off
	v_lshlrev_b64 v[16:17], 9, v[50:51]
	v_lshl_add_u64 v[16:17], v[34:35], 0, v[16:17]
	v_or_b32_e32 v50, 34, v32
	global_store_dword v[16:17], v1, off
	v_lshlrev_b64 v[0:1], 9, v[50:51]
	v_lshl_add_u64 v[0:1], v[34:35], 0, v[0:1]
	v_or_b32_e32 v50, 35, v32
	global_store_dword v[0:1], v2, off
	v_lshlrev_b64 v[0:1], 9, v[50:51]
	v_lshl_add_u64 v[0:1], v[34:35], 0, v[0:1]
	v_or_b32_e32 v50, 40, v32
	global_store_dword v[0:1], v3, off
	v_lshlrev_b64 v[0:1], 9, v[50:51]
	v_lshl_add_u64 v[0:1], v[34:35], 0, v[0:1]
	v_or_b32_e32 v50, 41, v32
	global_store_dword v[0:1], v4, off
	v_lshlrev_b64 v[0:1], 9, v[50:51]
	v_lshl_add_u64 v[0:1], v[34:35], 0, v[0:1]
	v_or_b32_e32 v50, 42, v32
	global_store_dword v[0:1], v5, off
	v_lshlrev_b64 v[0:1], 9, v[50:51]
	v_lshl_add_u64 v[0:1], v[34:35], 0, v[0:1]
	v_or_b32_e32 v50, 43, v32
	global_store_dword v[0:1], v6, off
	v_lshlrev_b64 v[0:1], 9, v[50:51]
	v_lshl_add_u64 v[0:1], v[34:35], 0, v[0:1]
	v_or_b32_e32 v50, 48, v32
	global_store_dword v[0:1], v7, off
	v_lshlrev_b64 v[0:1], 9, v[50:51]
	v_lshl_add_u64 v[0:1], v[34:35], 0, v[0:1]
	v_or_b32_e32 v50, 49, v32
	global_store_dword v[0:1], v8, off
	v_lshlrev_b64 v[0:1], 9, v[50:51]
	v_lshl_add_u64 v[0:1], v[34:35], 0, v[0:1]
	v_or_b32_e32 v50, 50, v32
	global_store_dword v[0:1], v9, off
	v_lshlrev_b64 v[0:1], 9, v[50:51]
	v_lshl_add_u64 v[0:1], v[34:35], 0, v[0:1]
	v_or_b32_e32 v50, 51, v32
	global_store_dword v[0:1], v10, off
	v_lshlrev_b64 v[0:1], 9, v[50:51]
	v_lshl_add_u64 v[0:1], v[34:35], 0, v[0:1]
	v_or_b32_e32 v50, 56, v32
	global_store_dword v[0:1], v11, off
	v_lshlrev_b64 v[0:1], 9, v[50:51]
	v_lshl_add_u64 v[0:1], v[34:35], 0, v[0:1]
	v_or_b32_e32 v50, 57, v32
	global_store_dword v[0:1], v12, off
	v_lshlrev_b64 v[0:1], 9, v[50:51]
	v_lshl_add_u64 v[0:1], v[34:35], 0, v[0:1]
	v_or_b32_e32 v50, 58, v32
	global_store_dword v[0:1], v13, off
	v_lshlrev_b64 v[0:1], 9, v[50:51]
	v_lshl_add_u64 v[0:1], v[34:35], 0, v[0:1]
	v_or_b32_e32 v50, 59, v32
	global_store_dword v[0:1], v14, off
	v_lshlrev_b64 v[0:1], 9, v[50:51]
	v_lshl_add_u64 v[0:1], v[34:35], 0, v[0:1]
	global_store_dword v[0:1], v15, off
